# attention body: cost-weighted VALU spacing (at most 3 v_exp per MFMA gap instead of bursts of 5)
# baseline (speedup 1.0000x reference)
.Lfa_body:
	s_waitcnt vmcnt(0) lgkmcnt(0)
	s_barrier
	s_and_b32 s10, s6, 0x8000
	s_add_i32 s9, s20, s10
	v_add_u32_e32 v0, s9, v156
	v_add_u32_e32 v2, v0, v148
	v_add_u32_e32 v3, v0, v150
	v_add_u32_e32 v4, v0, v152
	v_add_u32_e32 v5, v0, v154
	ds_read_b128 v[160:163], v2
	ds_read_b128 v[164:167], v2 offset:8192
	ds_read_b128 v[168:171], v3
	ds_read_b128 v[224:227], v3 offset:8192
	ds_read_b128 v[228:231], v4
	ds_read_b128 v[232:235], v4 offset:8192
	ds_read_b128 v[236:239], v5
	ds_read_b128 v[244:247], v5 offset:8192
	ds_read_b128 v[248:251], v2 offset:16384
	ds_read_b128 v[252:255], v2 offset:24576
	s_mov_b64 s[18:19], 0
	s_mov_b32 s80, 0
	s_waitcnt lgkmcnt(8)
	v_mfma_f32_32x32x16_bf16 v[96:111], v[160:163], v[128:131], v[80:95]
	ds_read_b128 v[160:163], v3 offset:16384
	s_xor_b32 s11, s10, 0x8000
	s_add_i32 s11, s11, s24
	s_sub_i32 s16, s8, 64
	s_mov_b32 s17, 0
	s_lshl_b64 s[16:17], s[16:17], 11
	s_mov_b32 m0, s11
	v_lshl_add_u64 v[10:11], v[144:145], 0, s[16:17]
	global_load_lds_dwordx4 v[10:11], off
	v_mfma_f32_32x32x16_bf16 v[112:127], v[164:167], v[128:131], v[80:95]
	ds_read_b128 v[164:167], v3 offset:24576
	v_add_u32_e32 v0, s9, v157
	v_add_u32_e32 v0, 0x10000, v0
	v_add_u32_e32 v6, v0, v149
	s_add_i32 m0, s11, 0x2000
	v_lshl_add_u64 v[10:11], v[10:11], 0, s[60:61]
	global_load_lds_dwordx4 v[10:11], off
	s_waitcnt lgkmcnt(8)
	v_mfma_f32_32x32x16_bf16 v[96:111], v[168:171], v[132:135], v[96:111]
	ds_read_b128 v[168:171], v4 offset:16384
	v_add_u32_e32 v7, v0, v151
	v_add_u32_e32 v8, v0, v153
	v_add_u32_e32 v9, v0, v155
	v_lshl_add_u64 v[12:13], v[146:147], 0, s[6:7]
	s_mov_b64 s[16:17], 0x6d08000
	s_add_i32 m0, s11, 0x10000
	v_lshl_add_u64 v[10:11], v[12:13], 0, s[16:17]
	global_load_lds_dwordx4 v[10:11], off
	v_mfma_f32_32x32x16_bf16 v[112:127], v[224:227], v[132:135], v[112:127]
	ds_read_b128 v[224:227], v4 offset:24576
	s_mov_b64 s[16:17], 0x6d0a000
	s_add_i32 m0, s11, 0x12000
	v_lshl_add_u64 v[10:11], v[12:13], 0, s[16:17]
	global_load_lds_dwordx4 v[10:11], off
	s_waitcnt lgkmcnt(8)
	v_mfma_f32_32x32x16_bf16 v[96:111], v[228:231], v[136:139], v[96:111]
	ds_read_b128 v[228:231], v5 offset:16384
	s_mov_b32 s16, s8
	s_mov_b32 s17, 0
	s_lshl_b64 s[16:17], s[16:17], 11
	s_add_i32 m0, s11, 0x4000
	v_lshl_add_u64 v[10:11], v[144:145], 0, s[16:17]
	global_load_lds_dwordx4 v[10:11], off
	v_mfma_f32_32x32x16_bf16 v[112:127], v[232:235], v[136:139], v[112:127]
	ds_read_b128 v[232:235], v5 offset:24576
	s_add_i32 m0, s11, 0x6000
	v_lshl_add_u64 v[10:11], v[10:11], 0, s[60:61]
	global_load_lds_dwordx4 v[10:11], off
	s_waitcnt lgkmcnt(8)
	v_mfma_f32_32x32x16_bf16 v[96:111], v[236:239], v[140:143], v[96:111]
	ds_read_b128 v[236:239], v6
	s_mov_b64 s[16:17], 0x6d0c000
	s_add_i32 m0, s11, 0x14000
	v_lshl_add_u64 v[10:11], v[12:13], 0, s[16:17]
	global_load_lds_dwordx4 v[10:11], off
	v_mfma_f32_32x32x16_bf16 v[112:127], v[244:247], v[140:143], v[112:127]
	ds_read_b128 v[244:247], v6 offset:4096
	s_mov_b64 s[16:17], 0x6d0e000
	s_add_i32 m0, s11, 0x16000
	v_lshl_add_u64 v[10:11], v[12:13], 0, s[16:17]
	global_load_lds_dwordx4 v[10:11], off
	s_waitcnt lgkmcnt(8)
	v_mfma_f32_32x32x16_bf16 v[192:207], v[248:251], v[128:131], v[80:95]
	ds_read_b128 v[248:251], v6 offset:8192
	v_max3_f32 v190, v96, v97, v98
	v_max3_f32 v190, v190, v99, v100
	v_max3_f32 v190, v190, v101, v102
	v_max3_f32 v190, v190, v103, v104
	v_mfma_f32_32x32x16_bf16 v[208:223], v[252:255], v[128:131], v[80:95]
	ds_read_b128 v[252:255], v6 offset:12288
	v_max3_f32 v190, v190, v105, v106
	v_max3_f32 v190, v190, v107, v108
	v_max3_f32 v190, v190, v109, v110
	v_max3_f32 v190, v190, v111, v111
	v_max3_f32 v191, v112, v113, v114
	v_max3_f32 v191, v191, v115, v116
	s_waitcnt lgkmcnt(8)
	v_mfma_f32_32x32x16_bf16 v[192:207], v[160:163], v[132:135], v[192:207]
	ds_read_b128 v[160:163], v7
	v_max3_f32 v191, v191, v117, v118
	v_max3_f32 v191, v191, v119, v120
	v_max3_f32 v191, v191, v121, v122
	v_max3_f32 v191, v191, v123, v124
	v_max3_f32 v191, v191, v125, v126
	v_max3_f32 v191, v191, v127, v127
	v_mfma_f32_32x32x16_bf16 v[208:223], v[164:167], v[132:135], v[208:223]
	ds_read_b128 v[164:167], v7 offset:4096
	v_max_f32_e32 v0, v190, v191
	v_mov_b32_e32 v15, v0
	s_nop 1
	v_permlane32_swap_b32_e32 v0, v15
	v_max_f32_e32 v0, v0, v15
	s_nop 0
	v_cmp_lt_f32_e32 vcc, s67, v0
	s_cbranch_vccnz .Lfa_rareA
.Lfa_retA:
	s_waitcnt lgkmcnt(8)
	v_mfma_f32_32x32x16_bf16 v[192:207], v[168:171], v[136:139], v[192:207]
	ds_read_b128 v[168:171], v7 offset:8192
	v_exp_f32_e32 v96, v96
	v_exp_f32_e32 v97, v97
	v_exp_f32_e32 v98, v98
	v_mfma_f32_32x32x16_bf16 v[208:223], v[224:227], v[136:139], v[208:223]
	ds_read_b128 v[224:227], v7 offset:12288
	v_exp_f32_e32 v99, v99
	v_exp_f32_e32 v100, v100
	v_add_f32_e32 v159, v159, v96
	v_add_f32_e32 v159, v159, v97
	v_add_f32_e32 v159, v159, v98
	s_waitcnt lgkmcnt(8)
	v_mfma_f32_32x32x16_bf16 v[192:207], v[228:231], v[140:143], v[192:207]
	ds_read_b128 v[228:231], v8
	v_exp_f32_e32 v101, v101
	v_exp_f32_e32 v102, v102
	v_add_f32_e32 v159, v159, v99
	v_add_f32_e32 v159, v159, v100
	v_cvt_pk_bf16_f32 v96, v96, v97
	v_cvt_pk_bf16_f32 v97, v98, v99
	v_mfma_f32_32x32x16_bf16 v[208:223], v[232:235], v[140:143], v[208:223]
	ds_read_b128 v[232:235], v8 offset:4096
	v_exp_f32_e32 v103, v103
	v_add_f32_e32 v159, v159, v101
	v_add_f32_e32 v159, v159, v102
	v_cvt_pk_bf16_f32 v98, v100, v101
	v_cvt_pk_bf16_f32 v99, v102, v103
	v_add_f32_e32 v159, v159, v103
	s_waitcnt lgkmcnt(8)
	v_mfma_f32_32x32x16_bf16 v[64:79], v[236:239], v[96:99], v[64:79]
	ds_read_b128 v[236:239], v8 offset:8192
	v_exp_f32_e32 v104, v104
	v_exp_f32_e32 v105, v105
	v_exp_f32_e32 v106, v106
	v_mfma_f32_32x32x16_bf16 v[48:63], v[244:247], v[96:99], v[48:63]
	ds_read_b128 v[244:247], v8 offset:12288
	v_exp_f32_e32 v107, v107
	v_exp_f32_e32 v108, v108
	v_add_f32_e32 v159, v159, v104
	v_add_f32_e32 v159, v159, v105
	v_add_f32_e32 v159, v159, v106
	s_waitcnt lgkmcnt(8)
	v_mfma_f32_32x32x16_bf16 v[32:47], v[248:251], v[96:99], v[32:47]
	ds_read_b128 v[248:251], v9
	v_exp_f32_e32 v109, v109
	v_exp_f32_e32 v110, v110
	v_add_f32_e32 v159, v159, v107
	v_add_f32_e32 v159, v159, v108
	v_cvt_pk_bf16_f32 v104, v104, v105
	v_cvt_pk_bf16_f32 v105, v106, v107
	v_mfma_f32_32x32x16_bf16 v[16:31], v[252:255], v[96:99], v[16:31]
	ds_read_b128 v[252:255], v9 offset:4096
	v_exp_f32_e32 v111, v111
	v_add_f32_e32 v159, v159, v109
	v_add_f32_e32 v159, v159, v110
	v_cvt_pk_bf16_f32 v106, v108, v109
	v_cvt_pk_bf16_f32 v107, v110, v111
	v_add_f32_e32 v159, v159, v111
	s_waitcnt lgkmcnt(8)
	v_mfma_f32_32x32x16_bf16 v[64:79], v[160:163], v[104:107], v[64:79]
	ds_read_b128 v[160:163], v9 offset:8192
	v_exp_f32_e32 v112, v112
	v_exp_f32_e32 v113, v113
	v_exp_f32_e32 v114, v114
	v_mfma_f32_32x32x16_bf16 v[48:63], v[164:167], v[104:107], v[48:63]
	ds_read_b128 v[164:167], v9 offset:12288
	v_exp_f32_e32 v115, v115
	v_exp_f32_e32 v116, v116
	v_add_f32_e32 v159, v159, v112
	v_add_f32_e32 v159, v159, v113
	v_add_f32_e32 v159, v159, v114
	s_waitcnt lgkmcnt(8)
	v_mfma_f32_32x32x16_bf16 v[32:47], v[168:171], v[104:107], v[32:47]
	ds_read_b128 v[168:171], v6 offset:16384
	v_exp_f32_e32 v117, v117
	v_exp_f32_e32 v118, v118
	v_add_f32_e32 v159, v159, v115
	v_add_f32_e32 v159, v159, v116
	v_cvt_pk_bf16_f32 v112, v112, v113
	v_cvt_pk_bf16_f32 v113, v114, v115
	v_mfma_f32_32x32x16_bf16 v[16:31], v[224:227], v[104:107], v[16:31]
	ds_read_b128 v[224:227], v6 offset:20480
	v_exp_f32_e32 v119, v119
	v_add_f32_e32 v159, v159, v117
	v_add_f32_e32 v159, v159, v118
	v_cvt_pk_bf16_f32 v114, v116, v117
	v_cvt_pk_bf16_f32 v115, v118, v119
	v_add_f32_e32 v159, v159, v119
	s_waitcnt lgkmcnt(8)
	v_mfma_f32_32x32x16_bf16 v[64:79], v[228:231], v[112:115], v[64:79]
	ds_read_b128 v[228:231], v6 offset:24576
	v_exp_f32_e32 v120, v120
	v_exp_f32_e32 v121, v121
	v_exp_f32_e32 v122, v122
	v_max3_f32 v190, v192, v193, v194
	v_max3_f32 v190, v190, v195, v196
	v_max3_f32 v190, v190, v197, v198
	v_max3_f32 v190, v190, v199, v200
	v_mfma_f32_32x32x16_bf16 v[48:63], v[232:235], v[112:115], v[48:63]
	ds_read_b128 v[232:235], v6 offset:28672
	v_exp_f32_e32 v123, v123
	v_exp_f32_e32 v124, v124
	v_add_f32_e32 v159, v159, v120
	v_add_f32_e32 v159, v159, v121
	v_add_f32_e32 v159, v159, v122
	v_max3_f32 v190, v190, v201, v202
	v_max3_f32 v190, v190, v203, v204
	v_max3_f32 v190, v190, v205, v206
	v_max3_f32 v190, v190, v207, v207
	s_waitcnt lgkmcnt(8)
	v_mfma_f32_32x32x16_bf16 v[32:47], v[236:239], v[112:115], v[32:47]
	ds_read_b128 v[236:239], v7 offset:16384
	v_exp_f32_e32 v125, v125
	v_exp_f32_e32 v126, v126
	v_add_f32_e32 v159, v159, v123
	v_add_f32_e32 v159, v159, v124
	v_cvt_pk_bf16_f32 v120, v120, v121
	v_cvt_pk_bf16_f32 v121, v122, v123
	v_max3_f32 v191, v208, v209, v210
	v_max3_f32 v191, v191, v211, v212
	v_max3_f32 v191, v191, v213, v214
	v_max3_f32 v191, v191, v215, v216
	v_mfma_f32_32x32x16_bf16 v[16:31], v[244:247], v[112:115], v[16:31]
	ds_read_b128 v[244:247], v7 offset:20480
	v_exp_f32_e32 v127, v127
	v_add_f32_e32 v159, v159, v125
	v_add_f32_e32 v159, v159, v126
	v_cvt_pk_bf16_f32 v122, v124, v125
	v_cvt_pk_bf16_f32 v123, v126, v127
	v_add_f32_e32 v159, v159, v127
	v_max3_f32 v191, v191, v217, v218
	v_max3_f32 v191, v191, v219, v220
	v_max3_f32 v191, v191, v221, v222
	v_max3_f32 v191, v191, v223, v223
	s_waitcnt lgkmcnt(8)
	v_mfma_f32_32x32x16_bf16 v[64:79], v[248:251], v[120:123], v[64:79]
	ds_read_b128 v[248:251], v7 offset:24576
	v_max_f32_e32 v0, v190, v191
	v_mov_b32_e32 v15, v0
	s_nop 1
	v_permlane32_swap_b32_e32 v0, v15
	v_max_f32_e32 v0, v0, v15
	s_nop 0
	v_cmp_lt_f32_e32 vcc, s67, v0
	s_or_b64 vcc, vcc, s[18:19]
	s_cbranch_vccnz .Lfa_rareB
.Lfa_retB:
	v_exp_f32_e32 v192, v192
	v_exp_f32_e32 v193, v193
	v_exp_f32_e32 v194, v194
	v_mfma_f32_32x32x16_bf16 v[48:63], v[252:255], v[120:123], v[48:63]
	ds_read_b128 v[252:255], v7 offset:28672
	v_exp_f32_e32 v195, v195
	v_exp_f32_e32 v196, v196
	v_add_f32_e32 v159, v159, v192
	v_add_f32_e32 v159, v159, v193
	v_add_f32_e32 v159, v159, v194
	s_waitcnt lgkmcnt(8)
	v_mfma_f32_32x32x16_bf16 v[32:47], v[160:163], v[120:123], v[32:47]
	ds_read_b128 v[160:163], v8 offset:16384
	v_exp_f32_e32 v197, v197
	v_exp_f32_e32 v198, v198
	v_add_f32_e32 v159, v159, v195
	v_add_f32_e32 v159, v159, v196
	v_cvt_pk_bf16_f32 v192, v192, v193
	v_cvt_pk_bf16_f32 v193, v194, v195
	v_mfma_f32_32x32x16_bf16 v[16:31], v[164:167], v[120:123], v[16:31]
	ds_read_b128 v[164:167], v8 offset:20480
	v_exp_f32_e32 v199, v199
	v_add_f32_e32 v159, v159, v197
	v_add_f32_e32 v159, v159, v198
	v_cvt_pk_bf16_f32 v194, v196, v197
	v_cvt_pk_bf16_f32 v195, v198, v199
	v_add_f32_e32 v159, v159, v199
	s_cmp_lg_u32 s80, 0
	s_cbranch_scc1 .Lfa_fixO
.Lfa_retO:
	s_waitcnt lgkmcnt(8)
	v_mfma_f32_32x32x16_bf16 v[64:79], v[168:171], v[192:195], v[64:79]
	ds_read_b128 v[168:171], v8 offset:24576
	v_exp_f32_e32 v200, v200
	v_exp_f32_e32 v201, v201
	v_exp_f32_e32 v202, v202
	v_mfma_f32_32x32x16_bf16 v[48:63], v[224:227], v[192:195], v[48:63]
	ds_read_b128 v[224:227], v8 offset:28672
	v_exp_f32_e32 v203, v203
	v_exp_f32_e32 v204, v204
	v_add_f32_e32 v159, v159, v200
	v_add_f32_e32 v159, v159, v201
	v_add_f32_e32 v159, v159, v202
	s_waitcnt lgkmcnt(8)
	v_mfma_f32_32x32x16_bf16 v[32:47], v[228:231], v[192:195], v[32:47]
	ds_read_b128 v[228:231], v9 offset:16384
	v_exp_f32_e32 v205, v205
	v_exp_f32_e32 v206, v206
	v_add_f32_e32 v159, v159, v203
	v_add_f32_e32 v159, v159, v204
	v_cvt_pk_bf16_f32 v200, v200, v201
	v_cvt_pk_bf16_f32 v201, v202, v203
	v_mfma_f32_32x32x16_bf16 v[16:31], v[232:235], v[192:195], v[16:31]
	ds_read_b128 v[232:235], v9 offset:20480
	v_exp_f32_e32 v207, v207
	v_add_f32_e32 v159, v159, v205
	v_add_f32_e32 v159, v159, v206
	v_cvt_pk_bf16_f32 v202, v204, v205
	v_cvt_pk_bf16_f32 v203, v206, v207
	v_add_f32_e32 v159, v159, v207
	s_waitcnt lgkmcnt(8)
	v_mfma_f32_32x32x16_bf16 v[64:79], v[236:239], v[200:203], v[64:79]
	ds_read_b128 v[236:239], v9 offset:24576
	v_exp_f32_e32 v208, v208
	v_exp_f32_e32 v209, v209
	v_exp_f32_e32 v210, v210
	v_mfma_f32_32x32x16_bf16 v[48:63], v[244:247], v[200:203], v[48:63]
	ds_read_b128 v[244:247], v9 offset:28672
	v_exp_f32_e32 v211, v211
	v_exp_f32_e32 v212, v212
	v_add_f32_e32 v159, v159, v208
	v_add_f32_e32 v159, v159, v209
	v_add_f32_e32 v159, v159, v210
	s_waitcnt lgkmcnt(8)
	v_mfma_f32_32x32x16_bf16 v[32:47], v[248:251], v[200:203], v[32:47]
	v_exp_f32_e32 v213, v213
	v_exp_f32_e32 v214, v214
	v_add_f32_e32 v159, v159, v211
	v_add_f32_e32 v159, v159, v212
	v_cvt_pk_bf16_f32 v208, v208, v209
	v_cvt_pk_bf16_f32 v209, v210, v211
	v_mfma_f32_32x32x16_bf16 v[16:31], v[252:255], v[200:203], v[16:31]
	v_exp_f32_e32 v215, v215
	v_add_f32_e32 v159, v159, v213
	v_add_f32_e32 v159, v159, v214
	v_cvt_pk_bf16_f32 v210, v212, v213
	v_cvt_pk_bf16_f32 v211, v214, v215
	v_add_f32_e32 v159, v159, v215
	s_waitcnt lgkmcnt(6)
	v_mfma_f32_32x32x16_bf16 v[64:79], v[160:163], v[208:211], v[64:79]
	v_exp_f32_e32 v216, v216
	v_exp_f32_e32 v217, v217
	v_exp_f32_e32 v218, v218
	v_mfma_f32_32x32x16_bf16 v[48:63], v[164:167], v[208:211], v[48:63]
	v_exp_f32_e32 v219, v219
	v_exp_f32_e32 v220, v220
	v_add_f32_e32 v159, v159, v216
	v_add_f32_e32 v159, v159, v217
	v_add_f32_e32 v159, v159, v218
	s_waitcnt lgkmcnt(4)
	v_mfma_f32_32x32x16_bf16 v[32:47], v[168:171], v[208:211], v[32:47]
	v_exp_f32_e32 v221, v221
	v_exp_f32_e32 v222, v222
	v_add_f32_e32 v159, v159, v219
	v_add_f32_e32 v159, v159, v220
	v_cvt_pk_bf16_f32 v216, v216, v217
	v_cvt_pk_bf16_f32 v217, v218, v219
	v_mfma_f32_32x32x16_bf16 v[16:31], v[224:227], v[208:211], v[16:31]
	v_exp_f32_e32 v223, v223
	v_add_f32_e32 v159, v159, v221
	v_add_f32_e32 v159, v159, v222
	v_cvt_pk_bf16_f32 v218, v220, v221
	v_cvt_pk_bf16_f32 v219, v222, v223
	v_add_f32_e32 v159, v159, v223
	s_waitcnt lgkmcnt(2)
	v_mfma_f32_32x32x16_bf16 v[64:79], v[228:231], v[216:219], v[64:79]
	s_add_i32 s26, s26, 1
	s_add_u32 s6, s6, 0x8000
	v_mfma_f32_32x32x16_bf16 v[48:63], v[232:235], v[216:219], v[48:63]
	s_addc_u32 s7, s7, 0
	s_addk_i32 s8, 0x80
	s_waitcnt lgkmcnt(0)
	v_mfma_f32_32x32x16_bf16 v[32:47], v[236:239], v[216:219], v[32:47]
	v_add_u32_e32 v158, 0xffffff80, v158
	v_mfma_f32_32x32x16_bf16 v[16:31], v[244:247], v[216:219], v[16:31]
	s_branch .LBB0_205
